# NA epilogue (4 copies): output stores paired through v_permlane32_swap into 4 dwordx4 per lane instead of 8 dwordx2
# speedup vs baseline: 1.0109x; 1.0033x over previous
.LBB0_1084:
	v_mov_b32_e32 v151, v149
	v_lshl_add_u64 v[32:33], s[94:95], 0, v[150:151]
	v_lshlrev_b32_e32 v34, 1, v144
	v_mov_b32_e32 v35, v149
	v_lshl_add_u64 v[32:33], v[32:33], 0, v[34:35]
	global_load_dwordx2 v[34:35], v[32:33], off
	v_bfe_u32 v198, v192, 5, 1
	v_lshlrev_b32_e32 v198, 3, v198
	v_mov_b32_e32 v199, 0
	v_lshl_add_u64 v[198:199], v[32:33], 0, v[198:199]
	global_load_dwordx2 v[240:241], v[32:33], off offset:16
	global_load_dwordx2 v[242:243], v[32:33], off offset:32
	global_load_dwordx2 v[244:245], v[32:33], off offset:48
	global_load_dwordx2 v[246:247], v[32:33], off offset:64
	global_load_dwordx2 v[248:249], v[32:33], off offset:80
	global_load_dwordx2 v[250:251], v[32:33], off offset:96
	global_load_dwordx2 v[252:253], v[32:33], off offset:112
	v_rcp_f32_e32 v36, v127
	s_waitcnt vmcnt(0)
	v_lshlrev_b32_e32 v37, 16, v34
	v_mul_f32_e32 v16, v16, v36
	v_mul_f32_e32 v17, v17, v36
	v_mul_f32_e32 v18, v18, v36
	v_mul_f32_e32 v19, v19, v36
	v_and_b32_e32 v34, 0xffff0000, v34
	v_lshlrev_b32_e32 v38, 16, v35
	v_and_b32_e32 v35, 0xffff0000, v35
	v_mul_f32_e32 v16, v16, v37
	v_mul_f32_e32 v17, v17, v34
	v_mul_f32_e32 v18, v18, v38
	v_mul_f32_e32 v19, v19, v35
	v_cvt_pk_bf16_f32 v16, v16, v17
	v_cvt_pk_bf16_f32 v17, v18, v19
	v_mul_f32_e32 v20, v20, v36
	v_mul_f32_e32 v21, v21, v36
	v_mul_f32_e32 v22, v22, v36
	v_mul_f32_e32 v23, v23, v36
	v_mov_b32_e32 v200, v16
	v_mov_b32_e32 v201, v17
	v_mul_f32_e32 v0, v0, v36
	v_mul_f32_e32 v1, v1, v36
	v_mul_f32_e32 v2, v2, v36
	v_mul_f32_e32 v3, v3, v36
	v_mul_f32_e32 v4, v4, v36
	v_mul_f32_e32 v5, v5, v36
	v_mul_f32_e32 v6, v6, v36
	v_mul_f32_e32 v7, v7, v36
	v_lshlrev_b32_e32 v16, 16, v240
	v_and_b32_e32 v17, 0xffff0000, v240
	v_lshlrev_b32_e32 v18, 16, v241
	v_and_b32_e32 v19, 0xffff0000, v241
	v_mul_f32_e32 v16, v20, v16
	v_mul_f32_e32 v17, v21, v17
	v_mul_f32_e32 v18, v22, v18
	v_mul_f32_e32 v19, v23, v19
	v_cvt_pk_bf16_f32 v16, v16, v17
	v_cvt_pk_bf16_f32 v17, v18, v19
	v_mul_f32_e32 v20, v24, v36
	v_mul_f32_e32 v21, v25, v36
	v_mul_f32_e32 v22, v26, v36
	v_mul_f32_e32 v23, v27, v36
	v_mov_b32_e32 v202, v16
	v_mov_b32_e32 v203, v17
	s_nop 1
	v_permlane32_swap_b32_e32 v200, v202
	v_permlane32_swap_b32_e32 v201, v203
	global_store_dwordx4 v[198:199], v[200:203], off
	v_lshlrev_b32_e32 v16, 16, v242
	v_and_b32_e32 v17, 0xffff0000, v242
	v_lshlrev_b32_e32 v18, 16, v243
	v_and_b32_e32 v19, 0xffff0000, v243
	v_mul_f32_e32 v16, v20, v16
	v_mul_f32_e32 v17, v21, v17
	v_mul_f32_e32 v18, v22, v18
	v_mul_f32_e32 v19, v23, v19
	v_cvt_pk_bf16_f32 v16, v16, v17
	v_cvt_pk_bf16_f32 v17, v18, v19
	v_mul_f32_e32 v20, v28, v36
	v_mul_f32_e32 v21, v29, v36
	v_mul_f32_e32 v22, v30, v36
	v_mul_f32_e32 v23, v31, v36
	v_mov_b32_e32 v200, v16
	v_mov_b32_e32 v201, v17
	v_lshlrev_b32_e32 v16, 16, v244
	v_and_b32_e32 v17, 0xffff0000, v244
	v_lshlrev_b32_e32 v18, 16, v245
	v_and_b32_e32 v19, 0xffff0000, v245
	v_mul_f32_e32 v16, v20, v16
	v_mul_f32_e32 v17, v21, v17
	v_mul_f32_e32 v18, v22, v18
	v_mul_f32_e32 v19, v23, v19
	v_cvt_pk_bf16_f32 v16, v16, v17
	v_cvt_pk_bf16_f32 v17, v18, v19
	s_nop 0
	v_mov_b32_e32 v202, v16
	v_mov_b32_e32 v203, v17
	s_nop 1
	v_permlane32_swap_b32_e32 v200, v202
	v_permlane32_swap_b32_e32 v201, v203
	global_store_dwordx4 v[198:199], v[200:203], off offset:32
	v_lshlrev_b32_e32 v16, 16, v246
	v_and_b32_e32 v17, 0xffff0000, v246
	v_lshlrev_b32_e32 v18, 16, v247
	v_and_b32_e32 v19, 0xffff0000, v247
	v_mul_f32_e32 v0, v0, v16
	v_mul_f32_e32 v1, v1, v17
	v_mul_f32_e32 v2, v2, v18
	v_mul_f32_e32 v3, v3, v19
	v_cvt_pk_bf16_f32 v0, v0, v1
	v_cvt_pk_bf16_f32 v1, v2, v3
	s_nop 0
	v_mov_b32_e32 v200, v0
	v_mov_b32_e32 v201, v1
	v_lshlrev_b32_e32 v0, 16, v248
	v_and_b32_e32 v1, 0xffff0000, v248
	v_lshlrev_b32_e32 v2, 16, v249
	v_and_b32_e32 v3, 0xffff0000, v249
	v_mul_f32_e32 v0, v4, v0
	v_mul_f32_e32 v1, v5, v1
	v_mul_f32_e32 v2, v6, v2
	v_mul_f32_e32 v3, v7, v3
	v_cvt_pk_bf16_f32 v0, v0, v1
	v_cvt_pk_bf16_f32 v1, v2, v3
	v_mul_f32_e32 v4, v8, v36
	v_mul_f32_e32 v5, v9, v36
	v_mul_f32_e32 v6, v10, v36
	v_mul_f32_e32 v7, v11, v36
	v_mov_b32_e32 v202, v0
	v_mov_b32_e32 v203, v1
	s_nop 1
	v_permlane32_swap_b32_e32 v200, v202
	v_permlane32_swap_b32_e32 v201, v203
	global_store_dwordx4 v[198:199], v[200:203], off offset:64
	v_lshlrev_b32_e32 v0, 16, v250
	v_and_b32_e32 v1, 0xffff0000, v250
	v_lshlrev_b32_e32 v2, 16, v251
	v_and_b32_e32 v3, 0xffff0000, v251
	v_mul_f32_e32 v0, v4, v0
	v_mul_f32_e32 v1, v5, v1
	v_mul_f32_e32 v2, v6, v2
	v_mul_f32_e32 v3, v7, v3
	v_cvt_pk_bf16_f32 v0, v0, v1
	v_cvt_pk_bf16_f32 v1, v2, v3
	v_mul_f32_e32 v4, v12, v36
	v_mul_f32_e32 v5, v13, v36
	v_mov_b32_e32 v200, v0
	v_mov_b32_e32 v201, v1
	v_mul_f32_e32 v6, v14, v36
	v_mul_f32_e32 v7, v15, v36
	v_lshlrev_b32_e32 v0, 16, v252
	v_and_b32_e32 v1, 0xffff0000, v252
	v_lshlrev_b32_e32 v2, 16, v253
	v_and_b32_e32 v3, 0xffff0000, v253
	v_mul_f32_e32 v0, v4, v0
	v_mul_f32_e32 v1, v5, v1
	v_mul_f32_e32 v2, v6, v2
	v_mul_f32_e32 v3, v7, v3
	v_cvt_pk_bf16_f32 v0, v0, v1
	v_cvt_pk_bf16_f32 v1, v2, v3
	v_mov_b32_e32 v202, v0
	v_mov_b32_e32 v203, v1
	s_nop 1
	v_permlane32_swap_b32_e32 v200, v202
	v_permlane32_swap_b32_e32 v201, v203
	global_store_dwordx4 v[198:199], v[200:203], off offset:96
	s_barrier

.LBB0_1319:
	v_mov_b32_e32 v151, v149
	v_lshl_add_u64 v[32:33], s[94:95], 0, v[150:151]
	v_lshlrev_b32_e32 v34, 1, v144
	v_mov_b32_e32 v35, v149
	v_lshl_add_u64 v[32:33], v[32:33], 0, v[34:35]
	global_load_dwordx2 v[34:35], v[32:33], off
	v_bfe_u32 v198, v192, 5, 1
	v_lshlrev_b32_e32 v198, 3, v198
	v_mov_b32_e32 v199, 0
	v_lshl_add_u64 v[198:199], v[32:33], 0, v[198:199]
	global_load_dwordx2 v[240:241], v[32:33], off offset:16
	global_load_dwordx2 v[242:243], v[32:33], off offset:32
	global_load_dwordx2 v[244:245], v[32:33], off offset:48
	global_load_dwordx2 v[246:247], v[32:33], off offset:64
	global_load_dwordx2 v[248:249], v[32:33], off offset:80
	global_load_dwordx2 v[250:251], v[32:33], off offset:96
	global_load_dwordx2 v[252:253], v[32:33], off offset:112
	v_rcp_f32_e32 v36, v176
	s_mov_b64 s[70:71], 0
	v_mul_f32_e32 v16, v16, v36
	v_mul_f32_e32 v17, v17, v36
	v_mul_f32_e32 v18, v18, v36
	v_mul_f32_e32 v19, v19, v36
	v_mul_f32_e32 v20, v20, v36
	v_mul_f32_e32 v21, v21, v36
	v_mul_f32_e32 v22, v22, v36
	v_mul_f32_e32 v23, v23, v36
	v_mul_f32_e32 v0, v0, v36
	v_mul_f32_e32 v1, v1, v36
	v_mul_f32_e32 v2, v2, v36
	v_mul_f32_e32 v3, v3, v36
	v_mul_f32_e32 v4, v4, v36
	v_mul_f32_e32 v5, v5, v36
	v_mul_f32_e32 v6, v6, v36
	v_mul_f32_e32 v7, v7, v36
	s_waitcnt vmcnt(0)
	v_lshlrev_b32_e32 v37, 16, v34
	v_and_b32_e32 v34, 0xffff0000, v34
	v_lshlrev_b32_e32 v38, 16, v35
	v_and_b32_e32 v35, 0xffff0000, v35
	v_mul_f32_e32 v16, v16, v37
	v_mul_f32_e32 v17, v17, v34
	v_mul_f32_e32 v18, v18, v38
	v_mul_f32_e32 v19, v19, v35
	v_cvt_pk_bf16_f32 v16, v16, v17
	v_cvt_pk_bf16_f32 v17, v18, v19
	s_nop 0
	v_mov_b32_e32 v200, v16
	v_mov_b32_e32 v201, v17
	v_lshlrev_b32_e32 v16, 16, v240
	v_and_b32_e32 v17, 0xffff0000, v240
	v_lshlrev_b32_e32 v18, 16, v241
	v_and_b32_e32 v19, 0xffff0000, v241
	v_mul_f32_e32 v16, v20, v16
	v_mul_f32_e32 v17, v21, v17
	v_mul_f32_e32 v18, v22, v18
	v_mul_f32_e32 v19, v23, v19
	v_cvt_pk_bf16_f32 v16, v16, v17
	v_cvt_pk_bf16_f32 v17, v18, v19
	v_mul_f32_e32 v20, v24, v36
	v_mul_f32_e32 v21, v25, v36
	v_mul_f32_e32 v22, v26, v36
	v_mul_f32_e32 v23, v27, v36
	v_mov_b32_e32 v202, v16
	v_mov_b32_e32 v203, v17
	s_nop 1
	v_permlane32_swap_b32_e32 v200, v202
	v_permlane32_swap_b32_e32 v201, v203
	global_store_dwordx4 v[198:199], v[200:203], off
	v_lshlrev_b32_e32 v16, 16, v242
	v_and_b32_e32 v17, 0xffff0000, v242
	v_lshlrev_b32_e32 v18, 16, v243
	v_and_b32_e32 v19, 0xffff0000, v243
	v_mul_f32_e32 v16, v20, v16
	v_mul_f32_e32 v17, v21, v17
	v_mul_f32_e32 v18, v22, v18
	v_mul_f32_e32 v19, v23, v19
	v_cvt_pk_bf16_f32 v16, v16, v17
	v_cvt_pk_bf16_f32 v17, v18, v19
	v_mul_f32_e32 v20, v28, v36
	v_mul_f32_e32 v21, v29, v36
	v_mul_f32_e32 v22, v30, v36
	v_mul_f32_e32 v23, v31, v36
	v_mov_b32_e32 v200, v16
	v_mov_b32_e32 v201, v17
	v_lshlrev_b32_e32 v16, 16, v244
	v_and_b32_e32 v17, 0xffff0000, v244
	v_lshlrev_b32_e32 v18, 16, v245
	v_and_b32_e32 v19, 0xffff0000, v245
	v_mul_f32_e32 v16, v20, v16
	v_mul_f32_e32 v17, v21, v17
	v_mul_f32_e32 v18, v22, v18
	v_mul_f32_e32 v19, v23, v19
	v_cvt_pk_bf16_f32 v16, v16, v17
	v_cvt_pk_bf16_f32 v17, v18, v19
	s_nop 0
	v_mov_b32_e32 v202, v16
	v_mov_b32_e32 v203, v17
	s_nop 1
	v_permlane32_swap_b32_e32 v200, v202
	v_permlane32_swap_b32_e32 v201, v203
	global_store_dwordx4 v[198:199], v[200:203], off offset:32
	v_lshlrev_b32_e32 v16, 16, v246
	v_and_b32_e32 v17, 0xffff0000, v246
	v_lshlrev_b32_e32 v18, 16, v247
	v_and_b32_e32 v19, 0xffff0000, v247
	v_mul_f32_e32 v0, v0, v16
	v_mul_f32_e32 v1, v1, v17
	v_mul_f32_e32 v2, v2, v18
	v_mul_f32_e32 v3, v3, v19
	v_cvt_pk_bf16_f32 v0, v0, v1
	v_cvt_pk_bf16_f32 v1, v2, v3
	s_nop 0
	v_mov_b32_e32 v200, v0
	v_mov_b32_e32 v201, v1
	v_lshlrev_b32_e32 v0, 16, v248
	v_and_b32_e32 v1, 0xffff0000, v248
	v_lshlrev_b32_e32 v2, 16, v249
	v_and_b32_e32 v3, 0xffff0000, v249
	v_mul_f32_e32 v0, v4, v0
	v_mul_f32_e32 v1, v5, v1
	v_mul_f32_e32 v2, v6, v2
	v_mul_f32_e32 v3, v7, v3
	v_cvt_pk_bf16_f32 v0, v0, v1
	v_cvt_pk_bf16_f32 v1, v2, v3
	v_mul_f32_e32 v4, v8, v36
	v_mul_f32_e32 v5, v9, v36
	v_mul_f32_e32 v6, v10, v36
	v_mul_f32_e32 v7, v11, v36
	v_mov_b32_e32 v202, v0
	v_mov_b32_e32 v203, v1
	s_nop 1
	v_permlane32_swap_b32_e32 v200, v202
	v_permlane32_swap_b32_e32 v201, v203
	global_store_dwordx4 v[198:199], v[200:203], off offset:64
	v_lshlrev_b32_e32 v0, 16, v250
	v_and_b32_e32 v1, 0xffff0000, v250
	v_lshlrev_b32_e32 v2, 16, v251
	v_and_b32_e32 v3, 0xffff0000, v251
	v_mul_f32_e32 v0, v4, v0
	v_mul_f32_e32 v1, v5, v1
	v_mul_f32_e32 v2, v6, v2
	v_mul_f32_e32 v3, v7, v3
	v_cvt_pk_bf16_f32 v0, v0, v1
	v_cvt_pk_bf16_f32 v1, v2, v3
	v_mul_f32_e32 v4, v12, v36
	v_mul_f32_e32 v5, v13, v36
	v_mov_b32_e32 v200, v0
	v_mov_b32_e32 v201, v1
	v_mul_f32_e32 v6, v14, v36
	v_mul_f32_e32 v7, v15, v36
	v_lshlrev_b32_e32 v0, 16, v252
	v_and_b32_e32 v1, 0xffff0000, v252
	v_lshlrev_b32_e32 v2, 16, v253
	v_and_b32_e32 v3, 0xffff0000, v253
	v_mul_f32_e32 v0, v4, v0
	v_mul_f32_e32 v1, v5, v1
	v_mul_f32_e32 v2, v6, v2
	v_mul_f32_e32 v3, v7, v3
	v_cvt_pk_bf16_f32 v0, v0, v1
	v_cvt_pk_bf16_f32 v1, v2, v3
	v_mov_b32_e32 v202, v0
	v_mov_b32_e32 v203, v1
	s_nop 1
	v_permlane32_swap_b32_e32 v200, v202
	v_permlane32_swap_b32_e32 v201, v203
	global_store_dwordx4 v[198:199], v[200:203], off offset:96
	s_barrier

.LBB0_1559:
	v_exp_f32_e32 v52, v64
	v_exp_f32_e32 v53, v65
	v_exp_f32_e32 v54, v66
	v_exp_f32_e32 v55, v67
	v_exp_f32_e32 v56, v68
	v_add_f32_e32 v49, v49, v50
	v_exp_f32_e32 v50, v32
	v_add_f32_e32 v32, 0, v52
	v_exp_f32_e32 v57, v69
	v_add_f32_e32 v32, v53, v32
	v_exp_f32_e32 v58, v70
	v_add_f32_e32 v32, v54, v32
	v_exp_f32_e32 v59, v71
	v_add_f32_e32 v32, v55, v32
	v_exp_f32_e32 v60, v72
	v_add_f32_e32 v32, v56, v32
	v_sub_f32_e32 v51, 0xf149f2ca, v111
	v_exp_f32_e32 v61, v73
	v_add_f32_e32 v32, v57, v32
	v_exp_f32_e32 v51, v51
	v_exp_f32_e32 v62, v74
	v_add_f32_e32 v32, v58, v32
	v_exp_f32_e32 v63, v75
	v_add_f32_e32 v32, v59, v32
	v_exp_f32_e32 v64, v76
	v_add_f32_e32 v32, v60, v32
	v_exp_f32_e32 v65, v77
	v_add_f32_e32 v32, v61, v32
	v_exp_f32_e32 v66, v78
	v_mul_f32_e32 v51, 0, v51
	v_add_f32_e32 v32, v62, v32
	v_exp_f32_e32 v67, v79
	v_add_f32_e32 v68, v115, v119
	v_cndmask_b32_e64 v51, v51, 0, s[2:3]
	v_add_f32_e32 v32, v63, v32
	v_add_f32_e32 v51, v51, v68
	v_add_f32_e32 v68, v121, v122
	v_add_f32_e32 v32, v64, v32
	v_fmac_f32_e32 v68, v51, v106
	v_exp_f32_e32 v51, v33
	v_add_f32_e32 v32, v65, v32
	v_fmac_f32_e32 v49, v68, v118
	v_exp_f32_e32 v68, v34
	v_add_f32_e32 v32, v66, v32
	v_exp_f32_e32 v69, v35
	v_add_f32_e32 v32, v67, v32
	v_exp_f32_e32 v70, v36
	v_add_f32_e32 v32, v50, v32
	v_exp_f32_e32 v71, v37
	v_add_f32_e32 v32, v51, v32
	v_exp_f32_e32 v72, v38
	v_add_f32_e32 v32, v68, v32
	v_exp_f32_e32 v73, v39
	v_add_f32_e32 v32, v69, v32
	v_exp_f32_e32 v74, v40
	v_add_f32_e32 v32, v70, v32
	v_exp_f32_e32 v75, v41
	v_add_f32_e32 v32, v71, v32
	v_exp_f32_e32 v76, v42
	v_add_f32_e32 v32, v72, v32
	v_exp_f32_e32 v77, v43
	v_add_f32_e32 v32, v73, v32
	v_exp_f32_e32 v78, v44
	v_add_f32_e32 v32, v74, v32
	v_exp_f32_e32 v79, v45
	v_add_f32_e32 v32, v75, v32
	v_exp_f32_e32 v80, v46
	v_add_f32_e32 v32, v76, v32
	v_exp_f32_e32 v47, v47
	v_add_f32_e32 v32, v77, v32
	v_add_f32_e32 v32, v78, v32
	v_add_f32_e32 v32, v79, v32
	v_add_f32_e32 v32, v80, v32
	v_add_f32_e32 v32, v47, v32
	v_mov_b32_e32 v33, v32
	s_nop 1
	v_permlane32_swap_b32_e32 v32, v33
	v_add_f32_e32 v81, v32, v33
	v_fmac_f32_e32 v81, v49, v48
	v_cvt_pk_bf16_f32 v32, v52, v53
	v_cvt_pk_bf16_f32 v33, v54, v55
	v_cvt_pk_bf16_f32 v34, v56, v57
	v_cvt_pk_bf16_f32 v35, v58, v59
	v_cvt_pk_bf16_f32 v36, v60, v61
	v_cvt_pk_bf16_f32 v37, v62, v63
	v_cvt_pk_bf16_f32 v38, v64, v65
	v_cvt_pk_bf16_f32 v39, v66, v67
	v_cvt_pk_bf16_f32 v40, v50, v51
	v_cvt_pk_bf16_f32 v41, v68, v69
	v_cvt_pk_bf16_f32 v42, v70, v71
	v_cvt_pk_bf16_f32 v43, v72, v73
	v_cvt_pk_bf16_f32 v44, v74, v75
	v_cvt_pk_bf16_f32 v45, v76, v77
	v_cvt_pk_bf16_f32 v46, v78, v79
	v_cvt_pk_bf16_f32 v47, v80, v47
	ds_read_b64_tr_b16 v[48:49], v125 offset:0
	ds_read_b64_tr_b16 v[50:51], v125 offset:0x400
	ds_read_b64_tr_b16 v[52:53], v125 offset:0x800
	ds_read_b64_tr_b16 v[54:55], v125 offset:0xc00
	ds_read_b64_tr_b16 v[56:57], v125 offset:0x1000
	ds_read_b64_tr_b16 v[58:59], v125 offset:0x1400
	ds_read_b64_tr_b16 v[60:61], v125 offset:0x1800
	ds_read_b64_tr_b16 v[62:63], v125 offset:0x1c00
	s_waitcnt lgkmcnt(0)
	s_nop 0
	v_mfma_f32_32x32x16_bf16 v[16:31], v[48:51], v[32:35], v[16:31]
	ds_read_b64_tr_b16 v[48:49], v125 offset:0x200
	ds_read_b64_tr_b16 v[50:51], v125 offset:0x600
	v_mfma_f32_32x32x16_bf16 v[16:31], v[52:55], v[36:39], v[16:31]
	ds_read_b64_tr_b16 v[52:53], v125 offset:0xa00
	ds_read_b64_tr_b16 v[54:55], v125 offset:0xe00
	v_mfma_f32_32x32x16_bf16 v[16:31], v[56:59], v[40:43], v[16:31]
	ds_read_b64_tr_b16 v[56:57], v125 offset:0x1200
	ds_read_b64_tr_b16 v[58:59], v125 offset:0x1600
	ds_read_b64_tr_b16 v[64:65], v125 offset:0x1a00
	ds_read_b64_tr_b16 v[66:67], v125 offset:0x1e00
	s_waitcnt lgkmcnt(0)
	v_mfma_f32_32x32x16_bf16 v[16:31], v[60:63], v[44:47], v[16:31]
	v_lshlrev_b32_e32 v106, 1, v104
	v_lshl_add_u64 v[60:61], s[0:1], 0, v[106:107]
	v_lshlrev_b32_e32 v106, 1, v144
	v_lshl_add_u64 v[60:61], v[60:61], 0, v[106:107]
	global_load_dwordx2 v[62:63], v[60:61], off
	v_bfe_u32 v198, v192, 5, 1
	v_lshlrev_b32_e32 v198, 3, v198
	v_mov_b32_e32 v199, 0
	v_lshl_add_u64 v[198:199], v[60:61], 0, v[198:199]
	global_load_dwordx2 v[240:241], v[60:61], off offset:16
	global_load_dwordx2 v[242:243], v[60:61], off offset:32
	global_load_dwordx2 v[244:245], v[60:61], off offset:48
	global_load_dwordx2 v[246:247], v[60:61], off offset:64
	global_load_dwordx2 v[248:249], v[60:61], off offset:80
	global_load_dwordx2 v[250:251], v[60:61], off offset:96
	global_load_dwordx2 v[252:253], v[60:61], off offset:112
	v_rcp_f32_e32 v68, v81
	v_mfma_f32_32x32x16_bf16 v[0:15], v[48:51], v[32:35], v[0:15]
	s_nop 4
	v_mul_f32_e32 v16, v68, v16
	v_mul_f32_e32 v17, v68, v17
	v_mul_f32_e32 v18, v68, v18
	v_mul_f32_e32 v19, v68, v19
	v_mul_f32_e32 v20, v68, v20
	v_mul_f32_e32 v21, v68, v21
	v_mul_f32_e32 v22, v68, v22
	v_mul_f32_e32 v23, v68, v23
	v_mfma_f32_32x32x16_bf16 v[0:15], v[52:55], v[36:39], v[0:15]
	s_waitcnt vmcnt(0)
	v_lshlrev_b32_e32 v69, 16, v62
	v_and_b32_e32 v62, 0xffff0000, v62
	v_lshlrev_b32_e32 v70, 16, v63
	v_and_b32_e32 v63, 0xffff0000, v63
	v_mul_f32_e32 v16, v16, v69
	v_mul_f32_e32 v17, v17, v62
	v_mul_f32_e32 v18, v18, v70
	v_mul_f32_e32 v19, v19, v63
	v_cvt_pk_bf16_f32 v16, v16, v17
	v_cvt_pk_bf16_f32 v17, v18, v19
	v_mfma_f32_32x32x16_bf16 v[0:15], v[56:59], v[40:43], v[0:15]
	v_mov_b32_e32 v200, v16
	v_mov_b32_e32 v201, v17
	v_lshlrev_b32_e32 v16, 16, v240
	v_and_b32_e32 v17, 0xffff0000, v240
	v_lshlrev_b32_e32 v18, 16, v241
	v_and_b32_e32 v19, 0xffff0000, v241
	v_mul_f32_e32 v16, v20, v16
	v_mul_f32_e32 v17, v21, v17
	v_mul_f32_e32 v18, v22, v18
	v_mul_f32_e32 v19, v23, v19
	v_cvt_pk_bf16_f32 v16, v16, v17
	v_cvt_pk_bf16_f32 v17, v18, v19
	v_mul_f32_e32 v20, v68, v24
	v_mul_f32_e32 v21, v68, v25
	v_mul_f32_e32 v22, v68, v26
	v_mul_f32_e32 v23, v68, v27
	v_mov_b32_e32 v202, v16
	v_mov_b32_e32 v203, v17
	s_nop 1
	v_permlane32_swap_b32_e32 v200, v202
	v_permlane32_swap_b32_e32 v201, v203
	global_store_dwordx4 v[198:199], v[200:203], off
	v_mfma_f32_32x32x16_bf16 v[0:15], v[64:67], v[44:47], v[0:15]
	v_lshlrev_b32_e32 v16, 16, v242
	v_and_b32_e32 v17, 0xffff0000, v242
	v_lshlrev_b32_e32 v18, 16, v243
	v_and_b32_e32 v19, 0xffff0000, v243
	v_mul_f32_e32 v16, v20, v16
	v_mul_f32_e32 v17, v21, v17
	v_mul_f32_e32 v18, v22, v18
	v_mul_f32_e32 v19, v23, v19
	v_cvt_pk_bf16_f32 v16, v16, v17
	v_cvt_pk_bf16_f32 v17, v18, v19
	v_mul_f32_e32 v20, v68, v28
	v_mul_f32_e32 v21, v68, v29
	v_mul_f32_e32 v22, v68, v30
	v_mul_f32_e32 v23, v68, v31
	v_mov_b32_e32 v200, v16
	v_mov_b32_e32 v201, v17
	v_mul_f32_e32 v0, v68, v0
	v_mul_f32_e32 v1, v68, v1
	v_mul_f32_e32 v2, v68, v2
	v_mul_f32_e32 v3, v68, v3
	v_mul_f32_e32 v4, v68, v4
	v_mul_f32_e32 v5, v68, v5
	v_mul_f32_e32 v6, v68, v6
	v_mul_f32_e32 v7, v68, v7
	v_lshlrev_b32_e32 v16, 16, v244
	v_and_b32_e32 v17, 0xffff0000, v244
	v_lshlrev_b32_e32 v18, 16, v245
	v_and_b32_e32 v19, 0xffff0000, v245
	v_mul_f32_e32 v16, v20, v16
	v_mul_f32_e32 v17, v21, v17
	v_mul_f32_e32 v18, v22, v18
	v_mul_f32_e32 v19, v23, v19
	v_cvt_pk_bf16_f32 v16, v16, v17
	v_cvt_pk_bf16_f32 v17, v18, v19
	s_nop 0
	v_mov_b32_e32 v202, v16
	v_mov_b32_e32 v203, v17
	s_nop 1
	v_permlane32_swap_b32_e32 v200, v202
	v_permlane32_swap_b32_e32 v201, v203
	global_store_dwordx4 v[198:199], v[200:203], off offset:32
	v_lshlrev_b32_e32 v16, 16, v246
	v_and_b32_e32 v17, 0xffff0000, v246
	v_lshlrev_b32_e32 v18, 16, v247
	v_and_b32_e32 v19, 0xffff0000, v247
	v_mul_f32_e32 v0, v0, v16
	v_mul_f32_e32 v1, v1, v17
	v_mul_f32_e32 v2, v2, v18
	v_mul_f32_e32 v3, v3, v19
	v_cvt_pk_bf16_f32 v0, v0, v1
	v_cvt_pk_bf16_f32 v1, v2, v3
	s_nop 0
	v_mov_b32_e32 v200, v0
	v_mov_b32_e32 v201, v1
	v_lshlrev_b32_e32 v0, 16, v248
	v_and_b32_e32 v1, 0xffff0000, v248
	v_lshlrev_b32_e32 v2, 16, v249
	v_and_b32_e32 v3, 0xffff0000, v249
	v_mul_f32_e32 v0, v4, v0
	v_mul_f32_e32 v1, v5, v1
	v_mul_f32_e32 v2, v6, v2
	v_mul_f32_e32 v3, v7, v3
	v_cvt_pk_bf16_f32 v0, v0, v1
	v_cvt_pk_bf16_f32 v1, v2, v3
	v_mul_f32_e32 v4, v68, v8
	v_mul_f32_e32 v5, v68, v9
	v_mul_f32_e32 v6, v68, v10
	v_mul_f32_e32 v7, v68, v11
	v_mov_b32_e32 v202, v0
	v_mov_b32_e32 v203, v1
	s_nop 1
	v_permlane32_swap_b32_e32 v200, v202
	v_permlane32_swap_b32_e32 v201, v203
	global_store_dwordx4 v[198:199], v[200:203], off offset:64
	v_lshlrev_b32_e32 v0, 16, v250
	v_and_b32_e32 v1, 0xffff0000, v250
	v_lshlrev_b32_e32 v2, 16, v251
	v_and_b32_e32 v3, 0xffff0000, v251
	v_mul_f32_e32 v0, v4, v0
	v_mul_f32_e32 v1, v5, v1
	v_mul_f32_e32 v2, v6, v2
	v_mul_f32_e32 v3, v7, v3
	v_cvt_pk_bf16_f32 v0, v0, v1
	v_cvt_pk_bf16_f32 v1, v2, v3
	v_mul_f32_e32 v4, v68, v12
	v_mul_f32_e32 v5, v68, v13
	v_mov_b32_e32 v200, v0
	v_mov_b32_e32 v201, v1
	v_mul_f32_e32 v6, v68, v14
	v_mul_f32_e32 v7, v68, v15
	v_lshlrev_b32_e32 v0, 16, v252
	v_and_b32_e32 v1, 0xffff0000, v252
	v_lshlrev_b32_e32 v2, 16, v253
	v_and_b32_e32 v3, 0xffff0000, v253
	v_mul_f32_e32 v0, v4, v0
	v_mul_f32_e32 v1, v5, v1
	v_mul_f32_e32 v2, v6, v2
	v_mul_f32_e32 v3, v7, v3
	v_cvt_pk_bf16_f32 v0, v0, v1
	v_cvt_pk_bf16_f32 v1, v2, v3
	v_mov_b32_e32 v202, v0
	v_mov_b32_e32 v203, v1
	s_nop 1
	v_permlane32_swap_b32_e32 v200, v202
	v_permlane32_swap_b32_e32 v201, v203
	global_store_dwordx4 v[198:199], v[200:203], off offset:96
	s_barrier

.LBB0_1571:
	v_exp_f32_e32 v52, v64
	v_exp_f32_e32 v53, v65
	v_exp_f32_e32 v54, v66
	v_exp_f32_e32 v55, v67
	v_exp_f32_e32 v56, v68
	v_add_f32_e32 v49, v49, v50
	v_exp_f32_e32 v50, v32
	v_add_f32_e32 v32, 0, v52
	v_exp_f32_e32 v57, v69
	v_add_f32_e32 v32, v53, v32
	v_exp_f32_e32 v58, v70
	v_add_f32_e32 v32, v54, v32
	v_exp_f32_e32 v59, v71
	v_add_f32_e32 v32, v55, v32
	v_exp_f32_e32 v60, v72
	v_add_f32_e32 v32, v56, v32
	v_sub_f32_e32 v51, 0xf149f2ca, v111
	v_exp_f32_e32 v61, v73
	v_add_f32_e32 v32, v57, v32
	v_exp_f32_e32 v51, v51
	v_exp_f32_e32 v62, v74
	v_add_f32_e32 v32, v58, v32
	v_exp_f32_e32 v63, v75
	v_add_f32_e32 v32, v59, v32
	v_exp_f32_e32 v64, v76
	v_add_f32_e32 v32, v60, v32
	v_exp_f32_e32 v65, v77
	v_add_f32_e32 v32, v61, v32
	v_exp_f32_e32 v66, v78
	v_mul_f32_e32 v51, 0, v51
	v_add_f32_e32 v32, v62, v32
	v_exp_f32_e32 v67, v79
	v_add_f32_e32 v68, v115, v133
	v_cndmask_b32_e64 v51, v51, 0, s[2:3]
	v_add_f32_e32 v32, v63, v32
	v_add_f32_e32 v51, v51, v68
	v_add_f32_e32 v68, v135, v136
	v_add_f32_e32 v32, v64, v32
	v_fmac_f32_e32 v68, v51, v106
	v_exp_f32_e32 v51, v33
	v_add_f32_e32 v32, v65, v32
	v_fmac_f32_e32 v49, v68, v124
	v_exp_f32_e32 v68, v34
	v_add_f32_e32 v32, v66, v32
	v_exp_f32_e32 v69, v35
	v_add_f32_e32 v32, v67, v32
	v_exp_f32_e32 v70, v36
	v_add_f32_e32 v32, v50, v32
	v_exp_f32_e32 v71, v37
	v_add_f32_e32 v32, v51, v32
	v_exp_f32_e32 v72, v38
	v_add_f32_e32 v32, v68, v32
	v_exp_f32_e32 v73, v39
	v_add_f32_e32 v32, v69, v32
	v_exp_f32_e32 v74, v40
	v_add_f32_e32 v32, v70, v32
	v_exp_f32_e32 v75, v41
	v_add_f32_e32 v32, v71, v32
	v_exp_f32_e32 v76, v42
	v_add_f32_e32 v32, v72, v32
	v_exp_f32_e32 v77, v43
	v_add_f32_e32 v32, v73, v32
	v_exp_f32_e32 v78, v44
	v_add_f32_e32 v32, v74, v32
	v_exp_f32_e32 v79, v45
	v_add_f32_e32 v32, v75, v32
	v_exp_f32_e32 v80, v46
	v_add_f32_e32 v32, v76, v32
	v_exp_f32_e32 v47, v47
	v_add_f32_e32 v32, v77, v32
	v_add_f32_e32 v32, v78, v32
	v_add_f32_e32 v32, v79, v32
	v_add_f32_e32 v32, v80, v32
	v_add_f32_e32 v32, v47, v32
	v_mov_b32_e32 v33, v32
	s_nop 1
	v_permlane32_swap_b32_e32 v32, v33
	v_add_f32_e32 v81, v32, v33
	v_fmac_f32_e32 v81, v49, v48
	v_cvt_pk_bf16_f32 v32, v52, v53
	v_cvt_pk_bf16_f32 v33, v54, v55
	v_cvt_pk_bf16_f32 v34, v56, v57
	v_cvt_pk_bf16_f32 v35, v58, v59
	v_cvt_pk_bf16_f32 v36, v60, v61
	v_cvt_pk_bf16_f32 v37, v62, v63
	v_cvt_pk_bf16_f32 v38, v64, v65
	v_cvt_pk_bf16_f32 v39, v66, v67
	v_cvt_pk_bf16_f32 v40, v50, v51
	v_cvt_pk_bf16_f32 v41, v68, v69
	v_cvt_pk_bf16_f32 v42, v70, v71
	v_cvt_pk_bf16_f32 v43, v72, v73
	v_cvt_pk_bf16_f32 v44, v74, v75
	v_cvt_pk_bf16_f32 v45, v76, v77
	v_cvt_pk_bf16_f32 v46, v78, v79
	v_cvt_pk_bf16_f32 v47, v80, v47
	ds_read_b64_tr_b16 v[48:49], v125 offset:0
	ds_read_b64_tr_b16 v[50:51], v125 offset:0x400
	ds_read_b64_tr_b16 v[52:53], v125 offset:0x800
	ds_read_b64_tr_b16 v[54:55], v125 offset:0xc00
	ds_read_b64_tr_b16 v[56:57], v125 offset:0x1000
	ds_read_b64_tr_b16 v[58:59], v125 offset:0x1400
	ds_read_b64_tr_b16 v[60:61], v125 offset:0x1800
	ds_read_b64_tr_b16 v[62:63], v125 offset:0x1c00
	s_waitcnt lgkmcnt(0)
	s_nop 0
	v_mfma_f32_32x32x16_bf16 v[16:31], v[48:51], v[32:35], v[16:31]
	ds_read_b64_tr_b16 v[48:49], v125 offset:0x200
	ds_read_b64_tr_b16 v[50:51], v125 offset:0x600
	v_mfma_f32_32x32x16_bf16 v[16:31], v[52:55], v[36:39], v[16:31]
	ds_read_b64_tr_b16 v[52:53], v125 offset:0xa00
	ds_read_b64_tr_b16 v[54:55], v125 offset:0xe00
	v_mfma_f32_32x32x16_bf16 v[16:31], v[56:59], v[40:43], v[16:31]
	ds_read_b64_tr_b16 v[56:57], v125 offset:0x1200
	ds_read_b64_tr_b16 v[58:59], v125 offset:0x1600
	ds_read_b64_tr_b16 v[64:65], v125 offset:0x1a00
	ds_read_b64_tr_b16 v[66:67], v125 offset:0x1e00
	s_waitcnt lgkmcnt(0)
	v_mfma_f32_32x32x16_bf16 v[16:31], v[60:63], v[44:47], v[16:31]
	v_lshlrev_b32_e32 v106, 1, v104
	v_lshl_add_u64 v[60:61], s[0:1], 0, v[106:107]
	v_lshlrev_b32_e32 v106, 1, v144
	v_lshl_add_u64 v[60:61], v[60:61], 0, v[106:107]
	global_load_dwordx2 v[62:63], v[60:61], off
	v_bfe_u32 v198, v192, 5, 1
	v_lshlrev_b32_e32 v198, 3, v198
	v_mov_b32_e32 v199, 0
	v_lshl_add_u64 v[198:199], v[60:61], 0, v[198:199]
	global_load_dwordx2 v[240:241], v[60:61], off offset:16
	global_load_dwordx2 v[242:243], v[60:61], off offset:32
	global_load_dwordx2 v[244:245], v[60:61], off offset:48
	global_load_dwordx2 v[246:247], v[60:61], off offset:64
	global_load_dwordx2 v[248:249], v[60:61], off offset:80
	global_load_dwordx2 v[250:251], v[60:61], off offset:96
	global_load_dwordx2 v[252:253], v[60:61], off offset:112
	v_rcp_f32_e32 v68, v81
	v_mfma_f32_32x32x16_bf16 v[0:15], v[48:51], v[32:35], v[0:15]
	s_mov_b64 s[2:3], 0
	s_nop 3
	v_mul_f32_e32 v16, v68, v16
	v_mul_f32_e32 v17, v68, v17
	v_mul_f32_e32 v18, v68, v18
	v_mul_f32_e32 v19, v68, v19
	v_mul_f32_e32 v20, v68, v20
	v_mul_f32_e32 v21, v68, v21
	v_mul_f32_e32 v22, v68, v22
	v_mul_f32_e32 v23, v68, v23
	v_mfma_f32_32x32x16_bf16 v[0:15], v[52:55], v[36:39], v[0:15]
	s_waitcnt vmcnt(0)
	v_lshlrev_b32_e32 v69, 16, v62
	v_and_b32_e32 v62, 0xffff0000, v62
	v_lshlrev_b32_e32 v70, 16, v63
	v_and_b32_e32 v63, 0xffff0000, v63
	v_mul_f32_e32 v16, v16, v69
	v_mul_f32_e32 v17, v17, v62
	v_mul_f32_e32 v18, v18, v70
	v_mul_f32_e32 v19, v19, v63
	v_cvt_pk_bf16_f32 v16, v16, v17
	v_cvt_pk_bf16_f32 v17, v18, v19
	v_mfma_f32_32x32x16_bf16 v[0:15], v[56:59], v[40:43], v[0:15]
	v_mov_b32_e32 v200, v16
	v_mov_b32_e32 v201, v17
	v_lshlrev_b32_e32 v16, 16, v240
	v_and_b32_e32 v17, 0xffff0000, v240
	v_lshlrev_b32_e32 v18, 16, v241
	v_and_b32_e32 v19, 0xffff0000, v241
	v_mul_f32_e32 v16, v20, v16
	v_mul_f32_e32 v17, v21, v17
	v_mul_f32_e32 v18, v22, v18
	v_mul_f32_e32 v19, v23, v19
	v_cvt_pk_bf16_f32 v16, v16, v17
	v_cvt_pk_bf16_f32 v17, v18, v19
	v_mul_f32_e32 v20, v68, v24
	v_mul_f32_e32 v21, v68, v25
	v_mul_f32_e32 v22, v68, v26
	v_mul_f32_e32 v23, v68, v27
	v_mov_b32_e32 v202, v16
	v_mov_b32_e32 v203, v17
	s_nop 1
	v_permlane32_swap_b32_e32 v200, v202
	v_permlane32_swap_b32_e32 v201, v203
	global_store_dwordx4 v[198:199], v[200:203], off
	v_mfma_f32_32x32x16_bf16 v[0:15], v[64:67], v[44:47], v[0:15]
	v_lshlrev_b32_e32 v16, 16, v242
	v_and_b32_e32 v17, 0xffff0000, v242
	v_lshlrev_b32_e32 v18, 16, v243
	v_and_b32_e32 v19, 0xffff0000, v243
	v_mul_f32_e32 v16, v20, v16
	v_mul_f32_e32 v17, v21, v17
	v_mul_f32_e32 v18, v22, v18
	v_mul_f32_e32 v19, v23, v19
	v_cvt_pk_bf16_f32 v16, v16, v17
	v_cvt_pk_bf16_f32 v17, v18, v19
	v_mul_f32_e32 v20, v68, v28
	v_mul_f32_e32 v21, v68, v29
	v_mul_f32_e32 v22, v68, v30
	v_mul_f32_e32 v23, v68, v31
	v_mov_b32_e32 v200, v16
	v_mov_b32_e32 v201, v17
	v_mul_f32_e32 v0, v68, v0
	v_mul_f32_e32 v1, v68, v1
	v_mul_f32_e32 v2, v68, v2
	v_mul_f32_e32 v3, v68, v3
	v_mul_f32_e32 v4, v68, v4
	v_mul_f32_e32 v5, v68, v5
	v_mul_f32_e32 v6, v68, v6
	v_mul_f32_e32 v7, v68, v7
	v_lshlrev_b32_e32 v16, 16, v244
	v_and_b32_e32 v17, 0xffff0000, v244
	v_lshlrev_b32_e32 v18, 16, v245
	v_and_b32_e32 v19, 0xffff0000, v245
	v_mul_f32_e32 v16, v20, v16
	v_mul_f32_e32 v17, v21, v17
	v_mul_f32_e32 v18, v22, v18
	v_mul_f32_e32 v19, v23, v19
	v_cvt_pk_bf16_f32 v16, v16, v17
	v_cvt_pk_bf16_f32 v17, v18, v19
	s_nop 0
	v_mov_b32_e32 v202, v16
	v_mov_b32_e32 v203, v17
	s_nop 1
	v_permlane32_swap_b32_e32 v200, v202
	v_permlane32_swap_b32_e32 v201, v203
	global_store_dwordx4 v[198:199], v[200:203], off offset:32
	v_lshlrev_b32_e32 v16, 16, v246
	v_and_b32_e32 v17, 0xffff0000, v246
	v_lshlrev_b32_e32 v18, 16, v247
	v_and_b32_e32 v19, 0xffff0000, v247
	v_mul_f32_e32 v0, v0, v16
	v_mul_f32_e32 v1, v1, v17
	v_mul_f32_e32 v2, v2, v18
	v_mul_f32_e32 v3, v3, v19
	v_cvt_pk_bf16_f32 v0, v0, v1
	v_cvt_pk_bf16_f32 v1, v2, v3
	s_nop 0
	v_mov_b32_e32 v200, v0
	v_mov_b32_e32 v201, v1
	v_lshlrev_b32_e32 v0, 16, v248
	v_and_b32_e32 v1, 0xffff0000, v248
	v_lshlrev_b32_e32 v2, 16, v249
	v_and_b32_e32 v3, 0xffff0000, v249
	v_mul_f32_e32 v0, v4, v0
	v_mul_f32_e32 v1, v5, v1
	v_mul_f32_e32 v2, v6, v2
	v_mul_f32_e32 v3, v7, v3
	v_cvt_pk_bf16_f32 v0, v0, v1
	v_cvt_pk_bf16_f32 v1, v2, v3
	v_mul_f32_e32 v4, v68, v8
	v_mul_f32_e32 v5, v68, v9
	v_mul_f32_e32 v6, v68, v10
	v_mul_f32_e32 v7, v68, v11
	v_mov_b32_e32 v202, v0
	v_mov_b32_e32 v203, v1
	s_nop 1
	v_permlane32_swap_b32_e32 v200, v202
	v_permlane32_swap_b32_e32 v201, v203
	global_store_dwordx4 v[198:199], v[200:203], off offset:64
	v_lshlrev_b32_e32 v0, 16, v250
	v_and_b32_e32 v1, 0xffff0000, v250
	v_lshlrev_b32_e32 v2, 16, v251
	v_and_b32_e32 v3, 0xffff0000, v251
	v_mul_f32_e32 v0, v4, v0
	v_mul_f32_e32 v1, v5, v1
	v_mul_f32_e32 v2, v6, v2
	v_mul_f32_e32 v3, v7, v3
	v_cvt_pk_bf16_f32 v0, v0, v1
	v_cvt_pk_bf16_f32 v1, v2, v3
	v_mul_f32_e32 v4, v68, v12
	v_mul_f32_e32 v5, v68, v13
	v_mov_b32_e32 v200, v0
	v_mov_b32_e32 v201, v1
	v_mul_f32_e32 v6, v68, v14
	v_mul_f32_e32 v7, v68, v15
	v_lshlrev_b32_e32 v0, 16, v252
	v_and_b32_e32 v1, 0xffff0000, v252
	v_lshlrev_b32_e32 v2, 16, v253
	v_and_b32_e32 v3, 0xffff0000, v253
	v_mul_f32_e32 v0, v4, v0
	v_mul_f32_e32 v1, v5, v1
	v_mul_f32_e32 v2, v6, v2
	v_mul_f32_e32 v3, v7, v3
	v_cvt_pk_bf16_f32 v0, v0, v1
	v_cvt_pk_bf16_f32 v1, v2, v3
	v_mov_b32_e32 v202, v0
	v_mov_b32_e32 v203, v1
	s_nop 1
	v_permlane32_swap_b32_e32 v200, v202
	v_permlane32_swap_b32_e32 v201, v203
	global_store_dwordx4 v[198:199], v[200:203], off offset:96
	s_barrier
